# grid barrier: the completing XCD releases all XCD generation words directly (one release hop less for other XCDs)
# baseline (speedup 1.0000x reference)
; __device__ __forceinline__ unsigned xb_ld(unsigned* p)              { return __hip_atomic_load(p, __ATOMIC_RELAXED, __HIP_MEMORY_SCOPE_AGENT); }
; __device__ __forceinline__ unsigned xb_add(unsigned* p, unsigned v) { return __hip_atomic_fetch_add(p, v, __ATOMIC_RELAXED, __HIP_MEMORY_SCOPE_AGENT); }
; #define XB_SPIN(cond, bar) do { unsigned _sp = 0; while (cond) { __builtin_amdgcn_s_sleep(1); \
;     if ((++_sp & 255u) == 0u) { if (xb_ld(&(bar)[XB_TMO])) break; if (_sp > XB_SPIN_CAP) { atomicAdd(&(bar)[XB_TMO], 1u); break; } } } } while (0)
; __device__ __forceinline__ void xcd_barrier(const XcdBarrier& b) {
;     ...
;     const unsigned old = xb_add(&bar[XB_XSUB(b.x)], 1u);
;     const unsigned gen = old / nloc;
;     if (old + 1u == (gen + 1u) * nloc) {
;       __builtin_amdgcn_fence(__ATOMIC_RELEASE, "agent");
;       asm volatile("s_waitcnt vmcnt(0)" ::: "memory");
;       const unsigned og = xb_add(&bar[XB_TOP], 1u);
;       const unsigned tg = og / nx;
;       if (og + 1u == (tg + 1u) * nx) xb_add(&bar[XB_TOPGEN], 1u);
;       else XB_SPIN(xb_ld(&bar[XB_TOPGEN]) == tg, bar);
.LBB0_1984:
	s_or_b64 exec, exec, s[10:11]
	s_waitcnt vmcnt(0)
	v_readfirstlane_b32 s8, v3
	v_sub_u32_e32 v4, 0, v2
	s_mov_b64 s[10:11], -1
	v_add_u32_e32 v3, s8, v0
	v_cvt_f32_u32_e32 v0, v2
	v_readlane_b32 s8, v252, 52
	v_readlane_b32 s9, v252, 53
	v_rcp_iflag_f32_e32 v0, v0
	s_nop 0
	v_mul_f32_e32 v0, 0x4f7ffffe, v0
	v_cvt_u32_f32_e32 v0, v0
	v_mul_lo_u32 v4, v4, v0
	v_mul_hi_u32 v4, v0, v4
	v_add_u32_e32 v0, v0, v4
	v_mul_hi_u32 v0, v3, v0
	v_mul_lo_u32 v4, v0, v2
	v_sub_u32_e32 v4, v3, v4
	v_cmp_ge_u32_e32 vcc, v4, v2
	v_add_u32_e32 v5, 1, v0
	v_add_u32_e32 v3, 1, v3
	v_cndmask_b32_e32 v0, v0, v5, vcc
	v_sub_u32_e32 v5, v4, v2
	v_cndmask_b32_e32 v4, v4, v5, vcc
	v_cmp_ge_u32_e32 vcc, v4, v2
	v_add_u32_e32 v4, 1, v0
	s_nop 0
	v_cndmask_b32_e32 v0, v0, v4, vcc
	v_mul_lo_u32 v4, v2, v0
	v_add_u32_e32 v2, v4, v2
	v_cmp_ne_u32_e32 vcc, v3, v2
	v_mov_b64_e32 v[2:3], s[8:9]
	s_and_b32 s100, exec_lo, vcc_lo
	s_and_saveexec_b64 s[8:9], vcc
	s_cbranch_execz .LBB0_1996
	v_readlane_b32 s10, v252, 52
	v_readlane_b32 s11, v252, 53
	s_mov_b64 s[12:13], 0
	s_nop 3
	global_load_dword v2, v1, s[10:11] sc1
	s_waitcnt vmcnt(0)
	v_cmp_eq_u32_e32 vcc, v2, v0
	s_and_saveexec_b64 s[10:11], vcc
	s_cbranch_execz .LBB0_1995
	s_mov_b32 s28, 1
	s_branch .LBB0_1988

; __device__ __forceinline__ unsigned xb_add(unsigned* p, unsigned v) { return __hip_atomic_fetch_add(p, v, __ATOMIC_RELAXED, __HIP_MEMORY_SCOPE_AGENT); }
; __device__ __forceinline__ void xcd_barrier(const XcdBarrier& b) {
;     ...
;       __builtin_amdgcn_fence(__ATOMIC_ACQUIRE, "agent");
;       xb_add(&bar[XB_XGEN(b.x)], 1u);
.LBB0_1998:
	s_or_b64 exec, exec, s[8:9]
	s_cmp_eq_u32 s100, 0
	s_cbranch_scc0 .Lxg_skip
	v_readlane_b32 s8, v252, 52
	v_readlane_b32 s9, v252, 53
	v_readlane_b32 s10, v252, 48
	v_readlane_b32 s11, v252, 49
	s_mov_b64 s[12:13], exec
	s_mov_b64 exec, 0xffff
	s_add_u32 s8, s8, 0xffffef00
	s_addc_u32 s9, s9, -1
	v_lshlrev_b32_e32 v4, 8, v168
	v_mov_b32_e32 v5, 0
	v_lshl_add_u64 v[4:5], v[4:5], 0, s[8:9]
	v_cmp_ne_u64_e32 vcc, s[10:11], v[4:5]
	s_and_b64 exec, exec, vcc
	v_mov_b32_e32 v6, 1
	global_atomic_add v[4:5], v6, off
	s_mov_b64 exec, s[12:13]
.Lxg_skip:
	s_mov_b64 s[8:9], exec
	v_mbcnt_lo_u32_b32 v0, s8, 0
	v_mbcnt_hi_u32_b32 v0, s9, v0
	v_cmp_eq_u32_e32 vcc, 0, v0
	s_waitcnt vmcnt(0)
	buffer_inv sc1
	s_and_saveexec_b64 s[10:11], vcc
	s_cbranch_execnz .LBB0_1999
	s_getpc_b64 s[98:99]

; __device__ __forceinline__ unsigned xb_add(unsigned* p, unsigned v) { return __hip_atomic_fetch_add(p, v, __ATOMIC_RELAXED, __HIP_MEMORY_SCOPE_AGENT); }
; __device__ __forceinline__ void xcd_barrier(const XcdBarrier& b) {
;     ...
;       xb_add(&bar[XB_XGEN(b.x)], 1u);
.LBB0_1999:
	s_cmp_eq_u32 s100, 0
	s_cbranch_scc0 .Lxg_tailskip
	s_bcnt1_i32_b64 s8, s[8:9]
	v_mov_b32_e32 v0, s8
	v_readlane_b32 s8, v252, 48
	v_readlane_b32 s9, v252, 49
	s_nop 4
	global_atomic_add v1, v0, s[8:9]
.Lxg_tailskip:
	s_getpc_b64 s[98:99]
